# W_up transposition moved from P0 into P1: workgroups with blockIdx bit 3 convert before their GEMM units, the others after, so the HBM-bound conversion overlaps the LDS-bound GEMM of the other half
# speedup vs baseline: 1.0055x; 1.0006x over previous
.LBB0_264:
	s_cmp_lt_i32 s86, 2
	s_cselect_b64 s[0:1], -1, 0
	s_cmp_gt_i32 s87, 1
	s_cselect_b64 s[2:3], -1, 0
	s_and_b64 s[0:1], s[0:1], s[2:3]
	s_andn2_b64 vcc, exec, s[0:1]
	s_cbranch_vccnz .LBB0_335
	s_mov_b32 s94, 2
	s_bitcmp1_b32 s33, 3
	s_cbranch_scc0 .Lmy_p1_pre
	s_mov_b32 s94, 0
.Lmy_p1_pre:
	s_cmp_eq_u32 s94, 0
	s_cbranch_scc1 .Lmy_wup_begin
	s_cmpk_gt_i32 s33, 0x2ff
	v_readfirstlane_b32 s1, v158
	s_cbranch_scc1 .LBB0_281
	v_lshrrev_b32_e32 v0, 5, v158
	v_lshrrev_b32_e32 v2, 1, v158
	v_and_b32_e32 v0, 4, v0
	v_bfe_u32 v1, v158, 2, 2
	v_and_b32_e32 v11, 24, v2
	v_or3_b32 v0, v0, v1, v11
	v_lshlrev_b32_e32 v1, 4, v158
	v_add_u32_e32 v8, 0x2000, v1
	v_lshrrev_b32_e32 v2, 7, v8
	s_movk_i32 s0, 0xe0
	v_and_b32_e32 v4, 32, v158
	s_waitcnt lgkmcnt(0)
	v_and_or_b32 v3, v2, s0, v0
	v_bitop3_b32 v9, v1, v4, 48 bitop3:0x6c
	v_and_b32_e32 v10, 64, v158
	v_bfe_u32 v12, v158, 2, 4
	s_movk_i32 s0, 0xf0
	v_or_b32_e32 v1, v9, v10
	v_and_or_b32 v2, v2, s0, v12
	s_add_u32 s30, s84, 0x7400000
	v_lshl_or_b32 v130, v2, 12, v1
	v_lshrrev_b32_e32 v2, 3, v158
	s_movk_i32 s0, 0x60
	s_addc_u32 s31, s85, 0
	v_and_or_b32 v0, v2, s0, v0
	s_movk_i32 s0, 0x70
	s_add_u32 s34, s84, 0x5c00000
	v_lshl_or_b32 v132, v0, 12, v1
	v_and_or_b32 v0, v2, s0, v12
	s_mul_hi_i32 s0, s33, 0x2aaaaaab
	s_addc_u32 s35, s85, 0
	s_lshr_b32 s2, s0, 31
	s_ashr_i32 s0, s0, 7
	s_add_i32 s2, s0, s2
	s_mul_i32 s0, s2, 0x300
	s_sub_i32 s0, s33, s0
	s_bfe_u32 s3, s0, 0x3001c
	s_add_i32 s3, s0, s3
	s_sext_i32_i16 s4, s3
	s_and_b32 s3, s3, 0xfff8
	s_lshr_b32 s8, s1, 6
	s_sub_i32 s0, s0, s3
	s_lshr_b32 s10, s1, 8
	s_lshl_b32 s36, s8, 10
	s_ashr_i32 s4, s4, 3
	s_sext_i32_i16 s3, s0
	s_cmp_lt_i32 s3, 0
	s_movk_i32 s37, 0x61
	s_cselect_b32 s3, s37, 0x60
	s_mul_i32 s0, s3, s0
	s_add_i32 s0, s0, s4
	s_sext_i32_i16 s3, s0
	s_mulk_i32 s3, 0x2aab
	s_lshr_b32 s4, s3, 31
	s_ashr_i32 s3, s3, 20
	s_add_i32 s3, s3, s4
	s_lshl_b32 s4, s3, 2
	s_mulk_i32 s3, 0x60
	s_sub_i32 s3, s0, s3
	s_bfe_i32 s0, s3, 0x80000
	s_bfe_u32 s0, s0, 0x2000d
	s_add_i32 s5, s3, s0
	s_bfe_i32 s0, s5, 0x80000
	s_and_b32 s5, s5, 0xfc
	s_sub_i32 s3, s3, s5
	s_sext_i32_i8 s3, s3
	s_add_i32 s22, s4, s3
	s_sext_i32_i16 s0, s0
	s_ashr_i32 s3, s2, 31
	s_ashr_i32 s23, s22, 31
	s_lshr_b32 s0, s0, 2
	s_lshl_b64 s[2:3], s[2:3], 12
	s_lshl_b64 s[4:5], s[22:23], 20
	s_add_u32 s6, s30, s4
	s_addc_u32 s7, s31, s5
	s_bfe_i64 s[4:5], s[0:1], 0x100000
	s_lshl_b64 s[4:5], s[4:5], 20
	s_add_u32 s4, s34, s4
	s_addc_u32 s5, s35, s5
	s_add_u32 s26, s4, s2
	s_addc_u32 s27, s5, s3
	s_add_i32 s23, s36, 0
	s_add_i32 m0, s23, 0x10000
	v_lshl_or_b32 v128, v3, 12, v1
	global_load_lds_dwordx4 v132, s[26:27]
	s_add_i32 m0, s23, 0x12000
	s_add_u32 s4, s26, 0x80000
	global_load_lds_dwordx4 v128, s[26:27]
	s_addc_u32 s5, s27, 0
	s_add_i32 m0, s23, 0x14000
	v_lshl_or_b32 v134, v0, 12, v1
	global_load_lds_dwordx4 v132, s[4:5]
	s_add_i32 m0, s23, 0x16000
	s_add_u32 s24, s6, s2
	s_addc_u32 s25, s7, s3
	s_add_i32 s38, s23, 0x2000
	global_load_lds_dwordx4 v128, s[4:5]
	s_mov_b32 m0, s23
	s_add_u32 s2, s24, 0x80000
	global_load_lds_dwordx4 v134, s[24:25]
	s_mov_b32 m0, s38
	s_addc_u32 s3, s25, 0
	s_add_i32 s39, s23, 0x4000
	global_load_lds_dwordx4 v130, s[24:25]
	s_mov_b32 m0, s39
	s_add_i32 s40, s23, 0x6000
	global_load_lds_dwordx4 v134, s[2:3]
	s_mov_b32 m0, s40
	v_mov_b32_e32 v133, 0
	global_load_lds_dwordx4 v130, s[2:3]
	v_mov_b32_e32 v129, v133
	v_mov_b32_e32 v135, v133
	v_mov_b32_e32 v131, v133
	s_cmp_eq_u32 s10, 1
	s_mov_b32 s41, 0
	v_lshl_add_u64 v[6:7], s[26:27], 0, v[132:133]
	v_lshl_add_u64 v[4:5], s[26:27], 0, v[128:129]
	v_lshl_add_u64 v[0:1], s[24:25], 0, v[134:135]
	s_cselect_b64 s[2:3], -1, 0
	s_cmp_lg_u32 s10, 1
	v_lshl_add_u64 v[2:3], s[24:25], 0, v[130:131]
	s_cbranch_scc1 .LBB0_268
	s_barrier

.LBB0_280:
	s_waitcnt vmcnt(0)
	s_barrier
.LBB0_281:
	s_cmp_eq_u32 s94, 1
	s_cbranch_scc1 .Lmy_p1_done
.Lmy_wup_begin:
	s_cmpk_lg_u32 s88, 0x100
	s_cbranch_scc1 .Lmy_wup_end
	s_waitcnt lgkmcnt(0)
	s_barrier
	v_readlane_b32 s2, v252, 0
	v_readlane_b32 s3, v252, 1
	s_add_u32 s2, s2, 0xffffff20
	s_addc_u32 s3, s3, -1
	s_load_dwordx4 s[4:7], s[2:3], 0xb0
	v_and_b32_e32 v197, 63, v158
	v_lshrrev_b32_e32 v198, 4, v197
	v_and_b32_e32 v194, 15, v197
	v_lshlrev_b32_e32 v194, 2, v194
	v_mul_u32_u24_e32 v193, 0x4100, v159
	v_mul_u32_u24_e32 v192, 65, v198
	v_add_u32_e32 v192, v192, v194
	v_lshl_add_u32 v176, v192, 2, v193
	v_add_u32_e32 v177, 0x410, v176
	v_add_u32_e32 v178, 0x820, v176
	v_add_u32_e32 v179, 0xc30, v176
	v_add_u32_e32 v180, 0x1040, v176
	v_add_u32_e32 v181, 0x1450, v176
	v_add_u32_e32 v182, 0x1860, v176
	v_add_u32_e32 v183, 0x1c70, v176
	v_add_u32_e32 v184, 0x2080, v176
	v_add_u32_e32 v185, 0x2490, v176
	v_add_u32_e32 v186, 0x28a0, v176
	v_add_u32_e32 v187, 0x2cb0, v176
	v_add_u32_e32 v188, 0x30c0, v176
	v_add_u32_e32 v189, 0x34d0, v176
	v_add_u32_e32 v190, 0x38e0, v176
	v_add_u32_e32 v191, 0x3cf0, v176
	v_lshlrev_b32_e32 v195, 2, v198
	v_lshlrev_b32_e32 v194, 2, v194
	v_lshl_add_u32 v194, v198, 15, v194
	v_and_b32_e32 v196, 7, v197
	v_mul_u32_u24_e32 v192, 0x208, v196
	v_lshrrev_b32_e32 v198, 3, v197
	v_add_u32_e32 v192, v192, v198
	v_lshl_add_u32 v192, v192, 2, v193
	v_add_u32_e32 v193, 0x400, v192
	v_lshlrev_b32_e32 v196, 4, v196
	v_lshl_add_u32 v196, v198, 12, v196
	v_readfirstlane_b32 s8, v159
	s_lshl_b32 s9, s33, 3
	s_add_i32 s8, s8, s9
	s_waitcnt lgkmcnt(0)
	s_lshr_b32 s9, s8, 7
	s_and_b32 s10, s8, 0x7f
	s_lshl_b32 s11, s9, 21
	s_lshl_b32 s12, s10, 8
	s_add_u32 s11, s11, s12
	s_add_u32 s16, s6, s11
	s_addc_u32 s17, s7, 0
	s_lshl_b32 s11, s9, 8
	s_add_u32 s18, s4, s11
	s_addc_u32 s19, s5, 0
	s_lshl_b32 s11, s10, 18
	s_lshl_b32 s12, s9, 7
	s_add_u32 s11, s11, s12
	s_add_u32 s11, s11, 0x1000000
	s_add_u32 s20, s84, s11
	s_addc_u32 s21, s85, 0
	s_addk_i32 s8, 0x800
	s_lshr_b32 s9, s8, 7
	s_and_b32 s10, s8, 0x7f
	s_lshl_b32 s11, s9, 21
	s_lshl_b32 s12, s10, 8
	s_add_u32 s11, s11, s12
	s_add_u32 s22, s6, s11
	s_addc_u32 s23, s7, 0
	s_lshl_b32 s11, s9, 8
	s_add_u32 s24, s4, s11
	s_addc_u32 s25, s5, 0
	s_lshl_b32 s11, s10, 18
	s_lshl_b32 s12, s9, 7
	s_add_u32 s11, s11, s12
	s_add_u32 s11, s11, 0x1000000
	s_add_u32 s26, s84, s11
	s_addc_u32 s27, s85, 0
	global_load_dword v128, v195, s[18:19]
	global_load_dword v129, v195, s[18:19] offset:16
	global_load_dword v130, v195, s[18:19] offset:32
	global_load_dword v131, v195, s[18:19] offset:48
	global_load_dword v132, v195, s[18:19] offset:64
	global_load_dword v133, v195, s[18:19] offset:80
	global_load_dword v134, v195, s[18:19] offset:96
	global_load_dword v135, v195, s[18:19] offset:112
	global_load_dword v136, v195, s[18:19] offset:128
	global_load_dword v137, v195, s[18:19] offset:144
	global_load_dword v138, v195, s[18:19] offset:160
	global_load_dword v139, v195, s[18:19] offset:176
	global_load_dword v140, v195, s[18:19] offset:192
	global_load_dword v141, v195, s[18:19] offset:208
	global_load_dword v142, v195, s[18:19] offset:224
	global_load_dword v143, v195, s[18:19] offset:240
	v_mov_b32_e32 v197, v194
	global_load_dwordx4 v[0:3], v197, s[16:17] nt
	v_add_u32_e32 v197, 0x20000, v197
	global_load_dwordx4 v[4:7], v197, s[16:17] nt
	v_add_u32_e32 v197, 0x20000, v197
	global_load_dwordx4 v[8:11], v197, s[16:17] nt
	v_add_u32_e32 v197, 0x20000, v197
	global_load_dwordx4 v[12:15], v197, s[16:17] nt
	v_add_u32_e32 v197, 0x20000, v197
	global_load_dwordx4 v[16:19], v197, s[16:17] nt
	v_add_u32_e32 v197, 0x20000, v197
	global_load_dwordx4 v[20:23], v197, s[16:17] nt
	v_add_u32_e32 v197, 0x20000, v197
	global_load_dwordx4 v[24:27], v197, s[16:17] nt
	v_add_u32_e32 v197, 0x20000, v197
	global_load_dwordx4 v[28:31], v197, s[16:17] nt
	v_add_u32_e32 v197, 0x20000, v197
	global_load_dwordx4 v[32:35], v197, s[16:17] nt
	v_add_u32_e32 v197, 0x20000, v197
	global_load_dwordx4 v[36:39], v197, s[16:17] nt
	v_add_u32_e32 v197, 0x20000, v197
	global_load_dwordx4 v[40:43], v197, s[16:17] nt
	v_add_u32_e32 v197, 0x20000, v197
	global_load_dwordx4 v[44:47], v197, s[16:17] nt
	v_add_u32_e32 v197, 0x20000, v197
	global_load_dwordx4 v[48:51], v197, s[16:17] nt
	v_add_u32_e32 v197, 0x20000, v197
	global_load_dwordx4 v[52:55], v197, s[16:17] nt
	v_add_u32_e32 v197, 0x20000, v197
	global_load_dwordx4 v[56:59], v197, s[16:17] nt
	v_add_u32_e32 v197, 0x20000, v197
	global_load_dwordx4 v[60:63], v197, s[16:17] nt
	global_load_dword v160, v195, s[24:25]
	global_load_dword v161, v195, s[24:25] offset:16
	global_load_dword v162, v195, s[24:25] offset:32
	global_load_dword v163, v195, s[24:25] offset:48
	global_load_dword v164, v195, s[24:25] offset:64
	global_load_dword v165, v195, s[24:25] offset:80
	global_load_dword v166, v195, s[24:25] offset:96
	global_load_dword v167, v195, s[24:25] offset:112
	global_load_dword v168, v195, s[24:25] offset:128
	global_load_dword v169, v195, s[24:25] offset:144
	global_load_dword v170, v195, s[24:25] offset:160
	global_load_dword v171, v195, s[24:25] offset:176
	global_load_dword v172, v195, s[24:25] offset:192
	global_load_dword v173, v195, s[24:25] offset:208
	global_load_dword v174, v195, s[24:25] offset:224
	global_load_dword v175, v195, s[24:25] offset:240
	v_mov_b32_e32 v197, v194
	global_load_dwordx4 v[64:67], v197, s[22:23] nt
	v_add_u32_e32 v197, 0x20000, v197
	global_load_dwordx4 v[68:71], v197, s[22:23] nt
	v_add_u32_e32 v197, 0x20000, v197
	global_load_dwordx4 v[72:75], v197, s[22:23] nt
	v_add_u32_e32 v197, 0x20000, v197
	global_load_dwordx4 v[76:79], v197, s[22:23] nt
	v_add_u32_e32 v197, 0x20000, v197
	global_load_dwordx4 v[80:83], v197, s[22:23] nt
	v_add_u32_e32 v197, 0x20000, v197
	global_load_dwordx4 v[84:87], v197, s[22:23] nt
	v_add_u32_e32 v197, 0x20000, v197
	global_load_dwordx4 v[88:91], v197, s[22:23] nt
	v_add_u32_e32 v197, 0x20000, v197
	global_load_dwordx4 v[92:95], v197, s[22:23] nt
	v_add_u32_e32 v197, 0x20000, v197
	global_load_dwordx4 v[96:99], v197, s[22:23] nt
	v_add_u32_e32 v197, 0x20000, v197
	global_load_dwordx4 v[100:103], v197, s[22:23] nt
	v_add_u32_e32 v197, 0x20000, v197
	global_load_dwordx4 v[104:107], v197, s[22:23] nt
	v_add_u32_e32 v197, 0x20000, v197
	global_load_dwordx4 v[108:111], v197, s[22:23] nt
	v_add_u32_e32 v197, 0x20000, v197
	global_load_dwordx4 v[112:115], v197, s[22:23] nt
	v_add_u32_e32 v197, 0x20000, v197
	global_load_dwordx4 v[116:119], v197, s[22:23] nt
	v_add_u32_e32 v197, 0x20000, v197
	global_load_dwordx4 v[120:123], v197, s[22:23] nt
	v_add_u32_e32 v197, 0x20000, v197
	global_load_dwordx4 v[124:127], v197, s[22:23] nt
	s_waitcnt vmcnt(47)
	v_mul_f32_e32 v0, v0, v128
	v_mul_f32_e32 v1, v1, v128
	v_mul_f32_e32 v2, v2, v128
	v_mul_f32_e32 v3, v3, v128
	ds_write2_b32 v176, v0, v1 offset1:1
	ds_write2_b32 v176, v2, v3 offset0:2 offset1:3
	s_waitcnt vmcnt(46)
	v_mul_f32_e32 v4, v4, v129
	v_mul_f32_e32 v5, v5, v129
	v_mul_f32_e32 v6, v6, v129
	v_mul_f32_e32 v7, v7, v129
	ds_write2_b32 v177, v4, v5 offset1:1
	ds_write2_b32 v177, v6, v7 offset0:2 offset1:3
	s_waitcnt vmcnt(45)
	v_mul_f32_e32 v8, v8, v130
	v_mul_f32_e32 v9, v9, v130
	v_mul_f32_e32 v10, v10, v130
	v_mul_f32_e32 v11, v11, v130
	ds_write2_b32 v178, v8, v9 offset1:1
	ds_write2_b32 v178, v10, v11 offset0:2 offset1:3
	s_waitcnt vmcnt(44)
	v_mul_f32_e32 v12, v12, v131
	v_mul_f32_e32 v13, v13, v131
	v_mul_f32_e32 v14, v14, v131
	v_mul_f32_e32 v15, v15, v131
	ds_write2_b32 v179, v12, v13 offset1:1
	ds_write2_b32 v179, v14, v15 offset0:2 offset1:3
	s_waitcnt vmcnt(43)
	v_mul_f32_e32 v16, v16, v132
	v_mul_f32_e32 v17, v17, v132
	v_mul_f32_e32 v18, v18, v132
	v_mul_f32_e32 v19, v19, v132
	ds_write2_b32 v180, v16, v17 offset1:1
	ds_write2_b32 v180, v18, v19 offset0:2 offset1:3
	s_waitcnt vmcnt(42)
	v_mul_f32_e32 v20, v20, v133
	v_mul_f32_e32 v21, v21, v133
	v_mul_f32_e32 v22, v22, v133
	v_mul_f32_e32 v23, v23, v133
	ds_write2_b32 v181, v20, v21 offset1:1
	ds_write2_b32 v181, v22, v23 offset0:2 offset1:3
	s_waitcnt vmcnt(41)
	v_mul_f32_e32 v24, v24, v134
	v_mul_f32_e32 v25, v25, v134
	v_mul_f32_e32 v26, v26, v134
	v_mul_f32_e32 v27, v27, v134
	ds_write2_b32 v182, v24, v25 offset1:1
	ds_write2_b32 v182, v26, v27 offset0:2 offset1:3
	s_waitcnt vmcnt(40)
	v_mul_f32_e32 v28, v28, v135
	v_mul_f32_e32 v29, v29, v135
	v_mul_f32_e32 v30, v30, v135
	v_mul_f32_e32 v31, v31, v135
	ds_write2_b32 v183, v28, v29 offset1:1
	ds_write2_b32 v183, v30, v31 offset0:2 offset1:3
	s_waitcnt vmcnt(39)
	v_mul_f32_e32 v32, v32, v136
	v_mul_f32_e32 v33, v33, v136
	v_mul_f32_e32 v34, v34, v136
	v_mul_f32_e32 v35, v35, v136
	ds_write2_b32 v184, v32, v33 offset1:1
	ds_write2_b32 v184, v34, v35 offset0:2 offset1:3
	s_waitcnt vmcnt(38)
	v_mul_f32_e32 v36, v36, v137
	v_mul_f32_e32 v37, v37, v137
	v_mul_f32_e32 v38, v38, v137
	v_mul_f32_e32 v39, v39, v137
	ds_write2_b32 v185, v36, v37 offset1:1
	ds_write2_b32 v185, v38, v39 offset0:2 offset1:3
	s_waitcnt vmcnt(37)
	v_mul_f32_e32 v40, v40, v138
	v_mul_f32_e32 v41, v41, v138
	v_mul_f32_e32 v42, v42, v138
	v_mul_f32_e32 v43, v43, v138
	ds_write2_b32 v186, v40, v41 offset1:1
	ds_write2_b32 v186, v42, v43 offset0:2 offset1:3
	s_waitcnt vmcnt(36)
	v_mul_f32_e32 v44, v44, v139
	v_mul_f32_e32 v45, v45, v139
	v_mul_f32_e32 v46, v46, v139
	v_mul_f32_e32 v47, v47, v139
	ds_write2_b32 v187, v44, v45 offset1:1
	ds_write2_b32 v187, v46, v47 offset0:2 offset1:3
	s_waitcnt vmcnt(35)
	v_mul_f32_e32 v48, v48, v140
	v_mul_f32_e32 v49, v49, v140
	v_mul_f32_e32 v50, v50, v140
	v_mul_f32_e32 v51, v51, v140
	ds_write2_b32 v188, v48, v49 offset1:1
	ds_write2_b32 v188, v50, v51 offset0:2 offset1:3
	s_waitcnt vmcnt(34)
	v_mul_f32_e32 v52, v52, v141
	v_mul_f32_e32 v53, v53, v141
	v_mul_f32_e32 v54, v54, v141
	v_mul_f32_e32 v55, v55, v141
	ds_write2_b32 v189, v52, v53 offset1:1
	ds_write2_b32 v189, v54, v55 offset0:2 offset1:3
	s_waitcnt vmcnt(33)
	v_mul_f32_e32 v56, v56, v142
	v_mul_f32_e32 v57, v57, v142
	v_mul_f32_e32 v58, v58, v142
	v_mul_f32_e32 v59, v59, v142
	ds_write2_b32 v190, v56, v57 offset1:1
	ds_write2_b32 v190, v58, v59 offset0:2 offset1:3
	s_waitcnt vmcnt(32)
	v_mul_f32_e32 v60, v60, v143
	v_mul_f32_e32 v61, v61, v143
	v_mul_f32_e32 v62, v62, v143
	v_mul_f32_e32 v63, v63, v143
	ds_write2_b32 v191, v60, v61 offset1:1
	ds_write2_b32 v191, v62, v63 offset0:2 offset1:3
	s_waitcnt lgkmcnt(0)
	v_mov_b32_e32 v197, v196
	ds_read2_b32 v[208:209], v192 offset0:0 offset1:65
	ds_read2_b32 v[210:211], v192 offset0:130 offset1:195
	ds_read2_b32 v[212:213], v193 offset0:4 offset1:69
	ds_read2_b32 v[214:215], v193 offset0:134 offset1:199
	ds_read2_b32 v[216:217], v192 offset0:8 offset1:73
	ds_read2_b32 v[218:219], v192 offset0:138 offset1:203
	ds_read2_b32 v[220:221], v193 offset0:12 offset1:77
	ds_read2_b32 v[222:223], v193 offset0:142 offset1:207
	s_waitcnt lgkmcnt(4)
	v_cvt_pk_bf16_f32 v200, v208, v209
	v_cvt_pk_bf16_f32 v201, v210, v211
	v_cvt_pk_bf16_f32 v202, v212, v213
	v_cvt_pk_bf16_f32 v203, v214, v215
	global_store_dwordx4 v197, v[200:203], s[20:21]
	v_add_u32_e32 v197, 0x8000, v197
	s_waitcnt lgkmcnt(0)
	v_cvt_pk_bf16_f32 v204, v216, v217
	v_cvt_pk_bf16_f32 v205, v218, v219
	v_cvt_pk_bf16_f32 v206, v220, v221
	v_cvt_pk_bf16_f32 v207, v222, v223
	global_store_dwordx4 v197, v[204:207], s[20:21]
	v_add_u32_e32 v197, 0x8000, v197
	ds_read2_b32 v[208:209], v192 offset0:16 offset1:81
	ds_read2_b32 v[210:211], v192 offset0:146 offset1:211
	ds_read2_b32 v[212:213], v193 offset0:20 offset1:85
	ds_read2_b32 v[214:215], v193 offset0:150 offset1:215
	ds_read2_b32 v[216:217], v192 offset0:24 offset1:89
	ds_read2_b32 v[218:219], v192 offset0:154 offset1:219
	ds_read2_b32 v[220:221], v193 offset0:28 offset1:93
	ds_read2_b32 v[222:223], v193 offset0:158 offset1:223
	s_waitcnt lgkmcnt(4)
	v_cvt_pk_bf16_f32 v200, v208, v209
	v_cvt_pk_bf16_f32 v201, v210, v211
	v_cvt_pk_bf16_f32 v202, v212, v213
	v_cvt_pk_bf16_f32 v203, v214, v215
	global_store_dwordx4 v197, v[200:203], s[20:21]
	v_add_u32_e32 v197, 0x8000, v197
	s_waitcnt lgkmcnt(0)
	v_cvt_pk_bf16_f32 v204, v216, v217
	v_cvt_pk_bf16_f32 v205, v218, v219
	v_cvt_pk_bf16_f32 v206, v220, v221
	v_cvt_pk_bf16_f32 v207, v222, v223
	global_store_dwordx4 v197, v[204:207], s[20:21]
	v_add_u32_e32 v197, 0x8000, v197
	ds_read2_b32 v[208:209], v192 offset0:32 offset1:97
	ds_read2_b32 v[210:211], v192 offset0:162 offset1:227
	ds_read2_b32 v[212:213], v193 offset0:36 offset1:101
	ds_read2_b32 v[214:215], v193 offset0:166 offset1:231
	ds_read2_b32 v[216:217], v192 offset0:40 offset1:105
	ds_read2_b32 v[218:219], v192 offset0:170 offset1:235
	ds_read2_b32 v[220:221], v193 offset0:44 offset1:109
	ds_read2_b32 v[222:223], v193 offset0:174 offset1:239
	s_waitcnt lgkmcnt(4)
	v_cvt_pk_bf16_f32 v200, v208, v209
	v_cvt_pk_bf16_f32 v201, v210, v211
	v_cvt_pk_bf16_f32 v202, v212, v213
	v_cvt_pk_bf16_f32 v203, v214, v215
	global_store_dwordx4 v197, v[200:203], s[20:21]
	v_add_u32_e32 v197, 0x8000, v197
	s_waitcnt lgkmcnt(0)
	v_cvt_pk_bf16_f32 v204, v216, v217
	v_cvt_pk_bf16_f32 v205, v218, v219
	v_cvt_pk_bf16_f32 v206, v220, v221
	v_cvt_pk_bf16_f32 v207, v222, v223
	global_store_dwordx4 v197, v[204:207], s[20:21]
	v_add_u32_e32 v197, 0x8000, v197
	ds_read2_b32 v[208:209], v192 offset0:48 offset1:113
	ds_read2_b32 v[210:211], v192 offset0:178 offset1:243
	ds_read2_b32 v[212:213], v193 offset0:52 offset1:117
	ds_read2_b32 v[214:215], v193 offset0:182 offset1:247
	ds_read2_b32 v[216:217], v192 offset0:56 offset1:121
	ds_read2_b32 v[218:219], v192 offset0:186 offset1:251
	ds_read2_b32 v[220:221], v193 offset0:60 offset1:125
	ds_read2_b32 v[222:223], v193 offset0:190 offset1:255
	s_waitcnt lgkmcnt(4)
	v_cvt_pk_bf16_f32 v200, v208, v209
	v_cvt_pk_bf16_f32 v201, v210, v211
	v_cvt_pk_bf16_f32 v202, v212, v213
	v_cvt_pk_bf16_f32 v203, v214, v215
	global_store_dwordx4 v197, v[200:203], s[20:21]
	v_add_u32_e32 v197, 0x8000, v197
	s_waitcnt lgkmcnt(0)
	v_cvt_pk_bf16_f32 v204, v216, v217
	v_cvt_pk_bf16_f32 v205, v218, v219
	v_cvt_pk_bf16_f32 v206, v220, v221
	v_cvt_pk_bf16_f32 v207, v222, v223
	global_store_dwordx4 v197, v[204:207], s[20:21]
	v_add_u32_e32 v197, 0x8000, v197
	s_waitcnt lgkmcnt(0)
	s_waitcnt vmcnt(23)
	v_mul_f32_e32 v64, v64, v160
	v_mul_f32_e32 v65, v65, v160
	v_mul_f32_e32 v66, v66, v160
	v_mul_f32_e32 v67, v67, v160
	ds_write2_b32 v176, v64, v65 offset1:1
	ds_write2_b32 v176, v66, v67 offset0:2 offset1:3
	s_waitcnt vmcnt(22)
	v_mul_f32_e32 v68, v68, v161
	v_mul_f32_e32 v69, v69, v161
	v_mul_f32_e32 v70, v70, v161
	v_mul_f32_e32 v71, v71, v161
	ds_write2_b32 v177, v68, v69 offset1:1
	ds_write2_b32 v177, v70, v71 offset0:2 offset1:3
	s_waitcnt vmcnt(21)
	v_mul_f32_e32 v72, v72, v162
	v_mul_f32_e32 v73, v73, v162
	v_mul_f32_e32 v74, v74, v162
	v_mul_f32_e32 v75, v75, v162
	ds_write2_b32 v178, v72, v73 offset1:1
	ds_write2_b32 v178, v74, v75 offset0:2 offset1:3
	s_waitcnt vmcnt(20)
	v_mul_f32_e32 v76, v76, v163
	v_mul_f32_e32 v77, v77, v163
	v_mul_f32_e32 v78, v78, v163
	v_mul_f32_e32 v79, v79, v163
	ds_write2_b32 v179, v76, v77 offset1:1
	ds_write2_b32 v179, v78, v79 offset0:2 offset1:3
	s_waitcnt vmcnt(19)
	v_mul_f32_e32 v80, v80, v164
	v_mul_f32_e32 v81, v81, v164
	v_mul_f32_e32 v82, v82, v164
	v_mul_f32_e32 v83, v83, v164
	ds_write2_b32 v180, v80, v81 offset1:1
	ds_write2_b32 v180, v82, v83 offset0:2 offset1:3
	s_waitcnt vmcnt(18)
	v_mul_f32_e32 v84, v84, v165
	v_mul_f32_e32 v85, v85, v165
	v_mul_f32_e32 v86, v86, v165
	v_mul_f32_e32 v87, v87, v165
	ds_write2_b32 v181, v84, v85 offset1:1
	ds_write2_b32 v181, v86, v87 offset0:2 offset1:3
	s_waitcnt vmcnt(17)
	v_mul_f32_e32 v88, v88, v166
	v_mul_f32_e32 v89, v89, v166
	v_mul_f32_e32 v90, v90, v166
	v_mul_f32_e32 v91, v91, v166
	ds_write2_b32 v182, v88, v89 offset1:1
	ds_write2_b32 v182, v90, v91 offset0:2 offset1:3
	s_waitcnt vmcnt(16)
	v_mul_f32_e32 v92, v92, v167
	v_mul_f32_e32 v93, v93, v167
	v_mul_f32_e32 v94, v94, v167
	v_mul_f32_e32 v95, v95, v167
	ds_write2_b32 v183, v92, v93 offset1:1
	ds_write2_b32 v183, v94, v95 offset0:2 offset1:3
	s_waitcnt vmcnt(15)
	v_mul_f32_e32 v96, v96, v168
	v_mul_f32_e32 v97, v97, v168
	v_mul_f32_e32 v98, v98, v168
	v_mul_f32_e32 v99, v99, v168
	ds_write2_b32 v184, v96, v97 offset1:1
	ds_write2_b32 v184, v98, v99 offset0:2 offset1:3
	s_waitcnt vmcnt(14)
	v_mul_f32_e32 v100, v100, v169
	v_mul_f32_e32 v101, v101, v169
	v_mul_f32_e32 v102, v102, v169
	v_mul_f32_e32 v103, v103, v169
	ds_write2_b32 v185, v100, v101 offset1:1
	ds_write2_b32 v185, v102, v103 offset0:2 offset1:3
	s_waitcnt vmcnt(13)
	v_mul_f32_e32 v104, v104, v170
	v_mul_f32_e32 v105, v105, v170
	v_mul_f32_e32 v106, v106, v170
	v_mul_f32_e32 v107, v107, v170
	ds_write2_b32 v186, v104, v105 offset1:1
	ds_write2_b32 v186, v106, v107 offset0:2 offset1:3
	s_waitcnt vmcnt(12)
	v_mul_f32_e32 v108, v108, v171
	v_mul_f32_e32 v109, v109, v171
	v_mul_f32_e32 v110, v110, v171
	v_mul_f32_e32 v111, v111, v171
	ds_write2_b32 v187, v108, v109 offset1:1
	ds_write2_b32 v187, v110, v111 offset0:2 offset1:3
	s_waitcnt vmcnt(11)
	v_mul_f32_e32 v112, v112, v172
	v_mul_f32_e32 v113, v113, v172
	v_mul_f32_e32 v114, v114, v172
	v_mul_f32_e32 v115, v115, v172
	ds_write2_b32 v188, v112, v113 offset1:1
	ds_write2_b32 v188, v114, v115 offset0:2 offset1:3
	s_waitcnt vmcnt(10)
	v_mul_f32_e32 v116, v116, v173
	v_mul_f32_e32 v117, v117, v173
	v_mul_f32_e32 v118, v118, v173
	v_mul_f32_e32 v119, v119, v173
	ds_write2_b32 v189, v116, v117 offset1:1
	ds_write2_b32 v189, v118, v119 offset0:2 offset1:3
	s_waitcnt vmcnt(9)
	v_mul_f32_e32 v120, v120, v174
	v_mul_f32_e32 v121, v121, v174
	v_mul_f32_e32 v122, v122, v174
	v_mul_f32_e32 v123, v123, v174
	ds_write2_b32 v190, v120, v121 offset1:1
	ds_write2_b32 v190, v122, v123 offset0:2 offset1:3
	s_waitcnt vmcnt(8)
	v_mul_f32_e32 v124, v124, v175
	v_mul_f32_e32 v125, v125, v175
	v_mul_f32_e32 v126, v126, v175
	v_mul_f32_e32 v127, v127, v175
	ds_write2_b32 v191, v124, v125 offset1:1
	ds_write2_b32 v191, v126, v127 offset0:2 offset1:3
	s_waitcnt lgkmcnt(0)
	v_mov_b32_e32 v197, v196
	ds_read2_b32 v[208:209], v192 offset0:0 offset1:65
	ds_read2_b32 v[210:211], v192 offset0:130 offset1:195
	ds_read2_b32 v[212:213], v193 offset0:4 offset1:69
	ds_read2_b32 v[214:215], v193 offset0:134 offset1:199
	ds_read2_b32 v[216:217], v192 offset0:8 offset1:73
	ds_read2_b32 v[218:219], v192 offset0:138 offset1:203
	ds_read2_b32 v[220:221], v193 offset0:12 offset1:77
	ds_read2_b32 v[222:223], v193 offset0:142 offset1:207
	s_waitcnt lgkmcnt(4)
	v_cvt_pk_bf16_f32 v200, v208, v209
	v_cvt_pk_bf16_f32 v201, v210, v211
	v_cvt_pk_bf16_f32 v202, v212, v213
	v_cvt_pk_bf16_f32 v203, v214, v215
	global_store_dwordx4 v197, v[200:203], s[26:27]
	v_add_u32_e32 v197, 0x8000, v197
	s_waitcnt lgkmcnt(0)
	v_cvt_pk_bf16_f32 v204, v216, v217
	v_cvt_pk_bf16_f32 v205, v218, v219
	v_cvt_pk_bf16_f32 v206, v220, v221
	v_cvt_pk_bf16_f32 v207, v222, v223
	global_store_dwordx4 v197, v[204:207], s[26:27]
	v_add_u32_e32 v197, 0x8000, v197
	ds_read2_b32 v[208:209], v192 offset0:16 offset1:81
	ds_read2_b32 v[210:211], v192 offset0:146 offset1:211
	ds_read2_b32 v[212:213], v193 offset0:20 offset1:85
	ds_read2_b32 v[214:215], v193 offset0:150 offset1:215
	ds_read2_b32 v[216:217], v192 offset0:24 offset1:89
	ds_read2_b32 v[218:219], v192 offset0:154 offset1:219
	ds_read2_b32 v[220:221], v193 offset0:28 offset1:93
	ds_read2_b32 v[222:223], v193 offset0:158 offset1:223
	s_waitcnt lgkmcnt(4)
	v_cvt_pk_bf16_f32 v200, v208, v209
	v_cvt_pk_bf16_f32 v201, v210, v211
	v_cvt_pk_bf16_f32 v202, v212, v213
	v_cvt_pk_bf16_f32 v203, v214, v215
	global_store_dwordx4 v197, v[200:203], s[26:27]
	v_add_u32_e32 v197, 0x8000, v197
	s_waitcnt lgkmcnt(0)
	v_cvt_pk_bf16_f32 v204, v216, v217
	v_cvt_pk_bf16_f32 v205, v218, v219
	v_cvt_pk_bf16_f32 v206, v220, v221
	v_cvt_pk_bf16_f32 v207, v222, v223
	global_store_dwordx4 v197, v[204:207], s[26:27]
	v_add_u32_e32 v197, 0x8000, v197
	ds_read2_b32 v[208:209], v192 offset0:32 offset1:97
	ds_read2_b32 v[210:211], v192 offset0:162 offset1:227
	ds_read2_b32 v[212:213], v193 offset0:36 offset1:101
	ds_read2_b32 v[214:215], v193 offset0:166 offset1:231
	ds_read2_b32 v[216:217], v192 offset0:40 offset1:105
	ds_read2_b32 v[218:219], v192 offset0:170 offset1:235
	ds_read2_b32 v[220:221], v193 offset0:44 offset1:109
	ds_read2_b32 v[222:223], v193 offset0:174 offset1:239
	s_waitcnt lgkmcnt(4)
	v_cvt_pk_bf16_f32 v200, v208, v209
	v_cvt_pk_bf16_f32 v201, v210, v211
	v_cvt_pk_bf16_f32 v202, v212, v213
	v_cvt_pk_bf16_f32 v203, v214, v215
	global_store_dwordx4 v197, v[200:203], s[26:27]
	v_add_u32_e32 v197, 0x8000, v197
	s_waitcnt lgkmcnt(0)
	v_cvt_pk_bf16_f32 v204, v216, v217
	v_cvt_pk_bf16_f32 v205, v218, v219
	v_cvt_pk_bf16_f32 v206, v220, v221
	v_cvt_pk_bf16_f32 v207, v222, v223
	global_store_dwordx4 v197, v[204:207], s[26:27]
	v_add_u32_e32 v197, 0x8000, v197
	ds_read2_b32 v[208:209], v192 offset0:48 offset1:113
	ds_read2_b32 v[210:211], v192 offset0:178 offset1:243
	ds_read2_b32 v[212:213], v193 offset0:52 offset1:117
	ds_read2_b32 v[214:215], v193 offset0:182 offset1:247
	ds_read2_b32 v[216:217], v192 offset0:56 offset1:121
	ds_read2_b32 v[218:219], v192 offset0:186 offset1:251
	ds_read2_b32 v[220:221], v193 offset0:60 offset1:125
	ds_read2_b32 v[222:223], v193 offset0:190 offset1:255
	s_waitcnt lgkmcnt(4)
	v_cvt_pk_bf16_f32 v200, v208, v209
	v_cvt_pk_bf16_f32 v201, v210, v211
	v_cvt_pk_bf16_f32 v202, v212, v213
	v_cvt_pk_bf16_f32 v203, v214, v215
	global_store_dwordx4 v197, v[200:203], s[26:27]
	v_add_u32_e32 v197, 0x8000, v197
	s_waitcnt lgkmcnt(0)
	v_cvt_pk_bf16_f32 v204, v216, v217
	v_cvt_pk_bf16_f32 v205, v218, v219
	v_cvt_pk_bf16_f32 v206, v220, v221
	v_cvt_pk_bf16_f32 v207, v222, v223
	global_store_dwordx4 v197, v[204:207], s[26:27]
	v_add_u32_e32 v197, 0x8000, v197
.Lmy_wup_end:
	s_cmp_eq_u32 s94, 0
	s_cbranch_scc0 .Lmy_p1_done
	s_mov_b32 s94, 1
	s_waitcnt vmcnt(0) lgkmcnt(0)
	s_barrier
	s_branch .Lmy_p1_pre
